# SwiGLU epilogue: output addressing via one 32-bit per-lane offset + saddr base (replaces 64-bit mov/mad/add per row block)
# speedup vs baseline: 1.0061x; 1.0061x over previous
.LBB0_264:
	s_lshl_b32 s11, s49, 7
	v_lshrrev_b32_e32 v138, 1, v145
	v_and_or_b32 v138, v138, 24, s11
	s_lshl_b32 s11, s24, 8
	s_add_i32 s11, s11, s44
	s_waitcnt lgkmcnt(0)
	v_pk_mul_f32 v[124:125], v[124:125], v[142:143] op_sel_hi:[1,0]
	v_or_b32_e32 v145, s11, v146
	v_mul_f32_e32 v146, 0xbfb8aa3b, v124
	v_mul_f32_e32 v147, 0xbfb8aa3b, v125
	v_exp_f32_e32 v146, v146
	v_exp_f32_e32 v147, v147
	v_pk_mul_f32 v[120:121], v[120:121], v[142:143] op_sel_hi:[1,0]
	v_pk_mul_f32 v[122:123], v[122:123], v[142:143] op_sel_hi:[1,0]
	v_add_f32_e32 v146, 1.0, v146
	v_add_f32_e32 v147, 1.0, v147
	v_rcp_f32_e32 v146, v146
	v_rcp_f32_e32 v147, v147
	v_pk_mul_f32 v[116:117], v[116:117], v[142:143] op_sel_hi:[1,0]
	v_pk_mul_f32 v[112:113], v[112:113], v[142:143] op_sel_hi:[1,0]
	v_pk_mul_f32 v[114:115], v[114:115], v[142:143] op_sel_hi:[1,0]
	v_pk_mul_f32 v[124:125], v[124:125], v[146:147]
	v_or_b32_e32 v138, s45, v138
	v_pk_mul_f32 v[120:121], v[120:121], v[124:125]
	v_pk_mul_f32 v[124:125], v[126:127], v[142:143] op_sel_hi:[1,0]
	v_ashrrev_i32_e32 v139, 31, v138
	v_mul_f32_e32 v126, 0xbfb8aa3b, v124
	v_mul_f32_e32 v127, 0xbfb8aa3b, v125
	v_exp_f32_e32 v126, v126
	v_exp_f32_e32 v127, v127
	s_and_b64 vcc, exec, s[0:1]
	v_add_f32_e32 v126, 1.0, v126
	v_add_f32_e32 v127, 1.0, v127
	v_rcp_f32_e32 v126, v126
	v_rcp_f32_e32 v127, v127
	s_nop 0
	v_pk_mul_f32 v[124:125], v[124:125], v[126:127]
	s_nop 0
	v_pk_mul_f32 v[122:123], v[122:123], v[124:125]
	v_mul_f32_e32 v124, 0xbfb8aa3b, v116
	v_mul_f32_e32 v125, 0xbfb8aa3b, v117
	v_exp_f32_e32 v124, v124
	v_exp_f32_e32 v125, v125
	v_add_f32_e32 v124, 1.0, v124
	v_add_f32_e32 v125, 1.0, v125
	v_rcp_f32_e32 v124, v124
	v_rcp_f32_e32 v125, v125
	s_nop 0
	v_pk_mul_f32 v[116:117], v[116:117], v[124:125]
	s_nop 0
	v_pk_mul_f32 v[116:117], v[112:113], v[116:117]
	v_pk_mul_f32 v[112:113], v[118:119], v[142:143] op_sel_hi:[1,0]
	s_nop 0
	v_mul_f32_e32 v118, 0xbfb8aa3b, v112
	v_mul_f32_e32 v119, 0xbfb8aa3b, v113
	v_exp_f32_e32 v118, v118
	v_exp_f32_e32 v119, v119
	v_add_f32_e32 v118, 1.0, v118
	v_add_f32_e32 v119, 1.0, v119
	v_rcp_f32_e32 v118, v118
	v_rcp_f32_e32 v119, v119
	s_nop 0
	v_pk_mul_f32 v[112:113], v[112:113], v[118:119]
	s_nop 0
	v_pk_mul_f32 v[118:119], v[114:115], v[112:113]
	v_mul_u32_u24_e32 v150, 0x1600, v145
	v_lshl_add_u32 v150, v138, 1, v150
	v_cvt_pk_bf16_f32 v112, v120, v121
	v_cvt_pk_bf16_f32 v113, v122, v123
	v_cvt_pk_bf16_f32 v114, v116, v117
	v_cvt_pk_bf16_f32 v115, v118, v119
	global_store_dwordx4 v150, v[112:115], s[6:7]
	s_cbranch_vccnz .LBB0_266
	ds_read_b32 v140, v144 offset:64
.LBB0_266:
	s_waitcnt lgkmcnt(0)
	v_pk_mul_f32 v[112:113], v[108:109], v[140:141] op_sel_hi:[1,0]
	v_pk_mul_f32 v[110:111], v[110:111], v[140:141] op_sel_hi:[1,0]
	v_mul_f32_e32 v108, 0xbfb8aa3b, v112
	v_exp_f32_e32 v109, v108
	v_pk_mul_f32 v[104:105], v[104:105], v[140:141] op_sel_hi:[1,0]
	v_pk_mul_f32 v[100:101], v[100:101], v[140:141] op_sel_hi:[1,0]
	v_pk_mul_f32 v[106:107], v[106:107], v[140:141] op_sel_hi:[1,0]
	v_add_f32_e32 v109, 1.0, v109
	v_rcp_f32_e32 v114, v109
	v_mul_f32_e32 v109, 0xbfb8aa3b, v113
	v_exp_f32_e32 v109, v109
	v_pk_mul_f32 v[96:97], v[96:97], v[140:141] op_sel_hi:[1,0]
	v_pk_mul_f32 v[98:99], v[98:99], v[140:141] op_sel_hi:[1,0]
	v_or_b32_e32 v116, 16, v145
	v_add_f32_e32 v109, 1.0, v109
	v_rcp_f32_e32 v115, v109
	v_mul_f32_e32 v109, 0xbfb8aa3b, v110
	v_exp_f32_e32 v109, v109
	v_mov_b32_e32 v108, 1.0
	v_pk_mul_f32 v[112:113], v[112:113], v[114:115]
	s_and_b64 vcc, exec, s[0:1]
	v_add_f32_e32 v109, 1.0, v109
	v_pk_mul_f32 v[104:105], v[104:105], v[112:113]
	v_rcp_f32_e32 v112, v109
	v_mul_f32_e32 v109, 0xbfb8aa3b, v111
	v_exp_f32_e32 v109, v109
	s_nop 0
	v_add_f32_e32 v109, 1.0, v109
	v_rcp_f32_e32 v113, v109
	v_mul_f32_e32 v109, 0xbfb8aa3b, v100
	v_exp_f32_e32 v109, v109
	v_pk_mul_f32 v[110:111], v[110:111], v[112:113]
	s_nop 0
	v_pk_mul_f32 v[106:107], v[106:107], v[110:111]
	v_add_f32_e32 v109, 1.0, v109
	v_rcp_f32_e32 v110, v109
	v_mul_f32_e32 v109, 0xbfb8aa3b, v101
	v_exp_f32_e32 v109, v109
	s_nop 0
	v_add_f32_e32 v109, 1.0, v109
	v_rcp_f32_e32 v111, v109
	s_nop 0
	v_pk_mul_f32 v[100:101], v[100:101], v[110:111]
	s_nop 0
	v_pk_mul_f32 v[100:101], v[96:97], v[100:101]
	v_pk_mul_f32 v[96:97], v[102:103], v[140:141] op_sel_hi:[1,0]
	s_nop 0
	v_mul_f32_e32 v102, 0xbfb8aa3b, v96
	v_mul_f32_e32 v103, 0xbfb8aa3b, v97
	v_exp_f32_e32 v102, v102
	v_exp_f32_e32 v103, v103
	v_add_f32_e32 v102, 1.0, v102
	v_add_f32_e32 v103, 1.0, v103
	v_rcp_f32_e32 v102, v102
	v_rcp_f32_e32 v103, v103
	s_nop 0
	v_pk_mul_f32 v[96:97], v[96:97], v[102:103]
	s_nop 0
	v_pk_mul_f32 v[102:103], v[98:99], v[96:97]
	v_add_u32_e32 v150, 0x16000, v150
	v_cvt_pk_bf16_f32 v96, v104, v105
	v_cvt_pk_bf16_f32 v97, v106, v107
	v_cvt_pk_bf16_f32 v98, v100, v101
	v_cvt_pk_bf16_f32 v99, v102, v103
	global_store_dwordx4 v150, v[96:99], s[6:7]
	s_nop 1
	v_mov_b32_e32 v96, 1.0
	s_cbranch_vccnz .LBB0_268
	ds_read_b32 v96, v144 offset:128
.LBB0_268:
	v_or_b32_e32 v97, 32, v145
	s_waitcnt lgkmcnt(0)
	v_pk_mul_f32 v[92:93], v[92:93], v[96:97] op_sel_hi:[1,0]
	v_pk_mul_f32 v[88:89], v[88:89], v[96:97] op_sel_hi:[1,0]
	v_mul_f32_e32 v98, 0xbfb8aa3b, v92
	v_mul_f32_e32 v99, 0xbfb8aa3b, v93
	v_exp_f32_e32 v98, v98
	v_exp_f32_e32 v99, v99
	v_pk_mul_f32 v[90:91], v[90:91], v[96:97] op_sel_hi:[1,0]
	v_pk_mul_f32 v[84:85], v[84:85], v[96:97] op_sel_hi:[1,0]
	v_add_f32_e32 v98, 1.0, v98
	v_add_f32_e32 v99, 1.0, v99
	v_rcp_f32_e32 v98, v98
	v_rcp_f32_e32 v99, v99
	v_pk_mul_f32 v[80:81], v[80:81], v[96:97] op_sel_hi:[1,0]
	v_pk_mul_f32 v[82:83], v[82:83], v[96:97] op_sel_hi:[1,0]
	s_and_b64 vcc, exec, s[0:1]
	v_pk_mul_f32 v[92:93], v[92:93], v[98:99]
	s_nop 0
	v_pk_mul_f32 v[88:89], v[88:89], v[92:93]
	v_pk_mul_f32 v[92:93], v[94:95], v[96:97] op_sel_hi:[1,0]
	s_nop 0
	v_mul_f32_e32 v94, 0xbfb8aa3b, v92
	v_mul_f32_e32 v95, 0xbfb8aa3b, v93
	v_exp_f32_e32 v94, v94
	v_exp_f32_e32 v95, v95
	v_add_f32_e32 v94, 1.0, v94
	v_add_f32_e32 v95, 1.0, v95
	v_rcp_f32_e32 v94, v94
	v_rcp_f32_e32 v95, v95
	s_nop 0
	v_pk_mul_f32 v[92:93], v[92:93], v[94:95]
	s_nop 0
	v_pk_mul_f32 v[90:91], v[90:91], v[92:93]
	v_mul_f32_e32 v92, 0xbfb8aa3b, v84
	v_mul_f32_e32 v93, 0xbfb8aa3b, v85
	v_exp_f32_e32 v92, v92
	v_exp_f32_e32 v93, v93
	v_add_f32_e32 v92, 1.0, v92
	v_add_f32_e32 v93, 1.0, v93
	v_rcp_f32_e32 v92, v92
	v_rcp_f32_e32 v93, v93
	s_nop 0
	v_pk_mul_f32 v[84:85], v[84:85], v[92:93]
	s_nop 0
	v_pk_mul_f32 v[84:85], v[80:81], v[84:85]
	v_pk_mul_f32 v[80:81], v[86:87], v[96:97] op_sel_hi:[1,0]
	s_nop 0
	v_mul_f32_e32 v86, 0xbfb8aa3b, v80
	v_mul_f32_e32 v87, 0xbfb8aa3b, v81
	v_exp_f32_e32 v86, v86
	v_exp_f32_e32 v87, v87
	v_add_f32_e32 v86, 1.0, v86
	v_add_f32_e32 v87, 1.0, v87
	v_rcp_f32_e32 v86, v86
	v_rcp_f32_e32 v87, v87
	s_nop 0
	v_pk_mul_f32 v[80:81], v[80:81], v[86:87]
	s_nop 0
	v_pk_mul_f32 v[86:87], v[82:83], v[80:81]
	v_add_u32_e32 v150, 0x16000, v150
	v_cvt_pk_bf16_f32 v80, v88, v89
	v_cvt_pk_bf16_f32 v81, v90, v91
	v_cvt_pk_bf16_f32 v82, v84, v85
	v_cvt_pk_bf16_f32 v83, v86, v87
	global_store_dwordx4 v150, v[80:83], s[6:7]
	s_cbranch_vccnz .LBB0_270
	ds_read_b32 v108, v144 offset:192
.LBB0_270:
	s_waitcnt lgkmcnt(0)
	v_pk_mul_f32 v[80:81], v[76:77], v[108:109] op_sel_hi:[1,0]
	v_pk_mul_f32 v[78:79], v[78:79], v[108:109] op_sel_hi:[1,0]
	v_mul_f32_e32 v76, 0xbfb8aa3b, v80
	v_exp_f32_e32 v77, v76
	v_pk_mul_f32 v[72:73], v[72:73], v[108:109] op_sel_hi:[1,0]
	v_pk_mul_f32 v[68:69], v[68:69], v[108:109] op_sel_hi:[1,0]
	v_pk_mul_f32 v[74:75], v[74:75], v[108:109] op_sel_hi:[1,0]
	v_add_f32_e32 v77, 1.0, v77
	v_rcp_f32_e32 v82, v77
	v_mul_f32_e32 v77, 0xbfb8aa3b, v81
	v_exp_f32_e32 v77, v77
	v_pk_mul_f32 v[64:65], v[64:65], v[108:109] op_sel_hi:[1,0]
	v_pk_mul_f32 v[66:67], v[66:67], v[108:109] op_sel_hi:[1,0]
	v_or_b32_e32 v84, 48, v145
	v_add_f32_e32 v77, 1.0, v77
	v_rcp_f32_e32 v83, v77
	v_mul_f32_e32 v77, 0xbfb8aa3b, v78
	v_exp_f32_e32 v77, v77
	v_mov_b32_e32 v76, 1.0
	v_pk_mul_f32 v[80:81], v[80:81], v[82:83]
	s_and_b64 vcc, exec, s[0:1]
	v_add_f32_e32 v77, 1.0, v77
	v_pk_mul_f32 v[72:73], v[72:73], v[80:81]
	v_rcp_f32_e32 v80, v77
	v_mul_f32_e32 v77, 0xbfb8aa3b, v79
	v_exp_f32_e32 v77, v77
	s_nop 0
	v_add_f32_e32 v77, 1.0, v77
	v_rcp_f32_e32 v81, v77
	v_mul_f32_e32 v77, 0xbfb8aa3b, v68
	v_exp_f32_e32 v77, v77
	v_pk_mul_f32 v[78:79], v[78:79], v[80:81]
	s_nop 0
	v_pk_mul_f32 v[74:75], v[74:75], v[78:79]
	v_add_f32_e32 v77, 1.0, v77
	v_rcp_f32_e32 v78, v77
	v_mul_f32_e32 v77, 0xbfb8aa3b, v69
	v_exp_f32_e32 v77, v77
	s_nop 0
	v_add_f32_e32 v77, 1.0, v77
	v_rcp_f32_e32 v79, v77
	s_nop 0
	v_pk_mul_f32 v[68:69], v[68:69], v[78:79]
	s_nop 0
	v_pk_mul_f32 v[68:69], v[64:65], v[68:69]
	v_pk_mul_f32 v[64:65], v[70:71], v[108:109] op_sel_hi:[1,0]
	s_nop 0
	v_mul_f32_e32 v70, 0xbfb8aa3b, v64
	v_mul_f32_e32 v71, 0xbfb8aa3b, v65
	v_exp_f32_e32 v70, v70
	v_exp_f32_e32 v71, v71
	v_add_f32_e32 v70, 1.0, v70
	v_add_f32_e32 v71, 1.0, v71
	v_rcp_f32_e32 v70, v70
	v_rcp_f32_e32 v71, v71
	s_nop 0
	v_pk_mul_f32 v[64:65], v[64:65], v[70:71]
	s_nop 0
	v_pk_mul_f32 v[70:71], v[66:67], v[64:65]
	v_add_u32_e32 v150, 0x16000, v150
	v_cvt_pk_bf16_f32 v64, v72, v73
	v_cvt_pk_bf16_f32 v65, v74, v75
	v_cvt_pk_bf16_f32 v66, v68, v69
	v_cvt_pk_bf16_f32 v67, v70, v71
	global_store_dwordx4 v150, v[64:67], s[6:7]
	s_nop 1
	v_mov_b32_e32 v64, 1.0
	s_cbranch_vccnz .LBB0_272
	ds_read_b32 v64, v144 offset:512
.LBB0_272:
	v_add_u32_e32 v65, 0x80, v145
	s_waitcnt lgkmcnt(0)
	v_pk_mul_f32 v[60:61], v[60:61], v[64:65] op_sel_hi:[1,0]
	v_pk_mul_f32 v[56:57], v[56:57], v[64:65] op_sel_hi:[1,0]
	v_mul_f32_e32 v66, 0xbfb8aa3b, v60
	v_mul_f32_e32 v67, 0xbfb8aa3b, v61
	v_exp_f32_e32 v66, v66
	v_exp_f32_e32 v67, v67
	v_pk_mul_f32 v[58:59], v[58:59], v[64:65] op_sel_hi:[1,0]
	v_pk_mul_f32 v[52:53], v[52:53], v[64:65] op_sel_hi:[1,0]
	v_add_f32_e32 v66, 1.0, v66
	v_add_f32_e32 v67, 1.0, v67
	v_rcp_f32_e32 v66, v66
	v_rcp_f32_e32 v67, v67
	v_pk_mul_f32 v[48:49], v[48:49], v[64:65] op_sel_hi:[1,0]
	v_pk_mul_f32 v[50:51], v[50:51], v[64:65] op_sel_hi:[1,0]
	s_and_b64 vcc, exec, s[0:1]
	v_pk_mul_f32 v[60:61], v[60:61], v[66:67]
	s_nop 0
	v_pk_mul_f32 v[56:57], v[56:57], v[60:61]
	v_pk_mul_f32 v[60:61], v[62:63], v[64:65] op_sel_hi:[1,0]
	s_nop 0
	v_mul_f32_e32 v62, 0xbfb8aa3b, v60
	v_mul_f32_e32 v63, 0xbfb8aa3b, v61
	v_exp_f32_e32 v62, v62
	v_exp_f32_e32 v63, v63
	v_add_f32_e32 v62, 1.0, v62
	v_add_f32_e32 v63, 1.0, v63
	v_rcp_f32_e32 v62, v62
	v_rcp_f32_e32 v63, v63
	s_nop 0
	v_pk_mul_f32 v[60:61], v[60:61], v[62:63]
	s_nop 0
	v_pk_mul_f32 v[58:59], v[58:59], v[60:61]
	v_mul_f32_e32 v60, 0xbfb8aa3b, v52
	v_mul_f32_e32 v61, 0xbfb8aa3b, v53
	v_exp_f32_e32 v60, v60
	v_exp_f32_e32 v61, v61
	v_add_f32_e32 v60, 1.0, v60
	v_add_f32_e32 v61, 1.0, v61
	v_rcp_f32_e32 v60, v60
	v_rcp_f32_e32 v61, v61
	s_nop 0
	v_pk_mul_f32 v[52:53], v[52:53], v[60:61]
	s_nop 0
	v_pk_mul_f32 v[52:53], v[48:49], v[52:53]
	v_pk_mul_f32 v[48:49], v[54:55], v[64:65] op_sel_hi:[1,0]
	s_nop 0
	v_mul_f32_e32 v54, 0xbfb8aa3b, v48
	v_mul_f32_e32 v55, 0xbfb8aa3b, v49
	v_exp_f32_e32 v54, v54
	v_exp_f32_e32 v55, v55
	v_add_f32_e32 v54, 1.0, v54
	v_add_f32_e32 v55, 1.0, v55
	v_rcp_f32_e32 v54, v54
	v_rcp_f32_e32 v55, v55
	s_nop 0
	v_pk_mul_f32 v[48:49], v[48:49], v[54:55]
	s_nop 0
	v_pk_mul_f32 v[54:55], v[50:51], v[48:49]
	v_add_u32_e32 v150, 0x6e000, v150
	v_cvt_pk_bf16_f32 v48, v56, v57
	v_cvt_pk_bf16_f32 v49, v58, v59
	v_cvt_pk_bf16_f32 v50, v52, v53
	v_cvt_pk_bf16_f32 v51, v54, v55
	global_store_dwordx4 v150, v[48:51], s[6:7]
	s_cbranch_vccnz .LBB0_274
	ds_read_b32 v76, v144 offset:576
.LBB0_274:
	s_waitcnt lgkmcnt(0)
	v_pk_mul_f32 v[48:49], v[44:45], v[76:77] op_sel_hi:[1,0]
	v_pk_mul_f32 v[46:47], v[46:47], v[76:77] op_sel_hi:[1,0]
	v_mul_f32_e32 v44, 0xbfb8aa3b, v48
	v_exp_f32_e32 v45, v44
	v_pk_mul_f32 v[40:41], v[40:41], v[76:77] op_sel_hi:[1,0]
	v_pk_mul_f32 v[36:37], v[36:37], v[76:77] op_sel_hi:[1,0]
	v_pk_mul_f32 v[42:43], v[42:43], v[76:77] op_sel_hi:[1,0]
	v_add_f32_e32 v45, 1.0, v45
	v_rcp_f32_e32 v50, v45
	v_mul_f32_e32 v45, 0xbfb8aa3b, v49
	v_exp_f32_e32 v45, v45
	v_pk_mul_f32 v[32:33], v[32:33], v[76:77] op_sel_hi:[1,0]
	v_pk_mul_f32 v[34:35], v[34:35], v[76:77] op_sel_hi:[1,0]
	v_add_u32_e32 v52, 0x90, v145
	v_add_f32_e32 v45, 1.0, v45
	v_rcp_f32_e32 v51, v45
	v_mul_f32_e32 v45, 0xbfb8aa3b, v46
	v_exp_f32_e32 v45, v45
	v_mov_b32_e32 v44, 1.0
	v_pk_mul_f32 v[48:49], v[48:49], v[50:51]
	s_and_b64 vcc, exec, s[0:1]
	v_add_f32_e32 v45, 1.0, v45
	v_pk_mul_f32 v[40:41], v[40:41], v[48:49]
	v_rcp_f32_e32 v48, v45
	v_mul_f32_e32 v45, 0xbfb8aa3b, v47
	v_exp_f32_e32 v45, v45
	s_nop 0
	v_add_f32_e32 v45, 1.0, v45
	v_rcp_f32_e32 v49, v45
	v_mul_f32_e32 v45, 0xbfb8aa3b, v36
	v_exp_f32_e32 v45, v45
	v_pk_mul_f32 v[46:47], v[46:47], v[48:49]
	s_nop 0
	v_pk_mul_f32 v[42:43], v[42:43], v[46:47]
	v_add_f32_e32 v45, 1.0, v45
	v_rcp_f32_e32 v46, v45
	v_mul_f32_e32 v45, 0xbfb8aa3b, v37
	v_exp_f32_e32 v45, v45
	s_nop 0
	v_add_f32_e32 v45, 1.0, v45
	v_rcp_f32_e32 v47, v45
	s_nop 0
	v_pk_mul_f32 v[36:37], v[36:37], v[46:47]
	s_nop 0
	v_pk_mul_f32 v[36:37], v[32:33], v[36:37]
	v_pk_mul_f32 v[32:33], v[38:39], v[76:77] op_sel_hi:[1,0]
	s_nop 0
	v_mul_f32_e32 v38, 0xbfb8aa3b, v32
	v_mul_f32_e32 v39, 0xbfb8aa3b, v33
	v_exp_f32_e32 v38, v38
	v_exp_f32_e32 v39, v39
	v_add_f32_e32 v38, 1.0, v38
	v_add_f32_e32 v39, 1.0, v39
	v_rcp_f32_e32 v38, v38
	v_rcp_f32_e32 v39, v39
	s_nop 0
	v_pk_mul_f32 v[32:33], v[32:33], v[38:39]
	s_nop 0
	v_pk_mul_f32 v[38:39], v[34:35], v[32:33]
	v_add_u32_e32 v150, 0x16000, v150
	v_cvt_pk_bf16_f32 v32, v40, v41
	v_cvt_pk_bf16_f32 v33, v42, v43
	v_cvt_pk_bf16_f32 v34, v36, v37
	v_cvt_pk_bf16_f32 v35, v38, v39
	global_store_dwordx4 v150, v[32:35], s[6:7]
	s_nop 1
	v_mov_b32_e32 v32, 1.0
	s_cbranch_vccnz .LBB0_276
	ds_read_b32 v32, v144 offset:640
.LBB0_276:
	v_add_u32_e32 v33, 0xa0, v145
	s_waitcnt lgkmcnt(0)
	v_pk_mul_f32 v[28:29], v[28:29], v[32:33] op_sel_hi:[1,0]
	v_pk_mul_f32 v[24:25], v[24:25], v[32:33] op_sel_hi:[1,0]
	v_mul_f32_e32 v34, 0xbfb8aa3b, v28
	v_mul_f32_e32 v35, 0xbfb8aa3b, v29
	v_exp_f32_e32 v34, v34
	v_exp_f32_e32 v35, v35
	v_pk_mul_f32 v[26:27], v[26:27], v[32:33] op_sel_hi:[1,0]
	v_pk_mul_f32 v[20:21], v[20:21], v[32:33] op_sel_hi:[1,0]
	v_add_f32_e32 v34, 1.0, v34
	v_add_f32_e32 v35, 1.0, v35
	v_rcp_f32_e32 v34, v34
	v_rcp_f32_e32 v35, v35
	v_pk_mul_f32 v[16:17], v[16:17], v[32:33] op_sel_hi:[1,0]
	v_pk_mul_f32 v[18:19], v[18:19], v[32:33] op_sel_hi:[1,0]
	s_and_b64 vcc, exec, s[0:1]
	v_pk_mul_f32 v[28:29], v[28:29], v[34:35]
	s_nop 0
	v_pk_mul_f32 v[24:25], v[24:25], v[28:29]
	v_pk_mul_f32 v[28:29], v[30:31], v[32:33] op_sel_hi:[1,0]
	s_nop 0
	v_mul_f32_e32 v30, 0xbfb8aa3b, v28
	v_mul_f32_e32 v31, 0xbfb8aa3b, v29
	v_exp_f32_e32 v30, v30
	v_exp_f32_e32 v31, v31
	v_add_f32_e32 v30, 1.0, v30
	v_add_f32_e32 v31, 1.0, v31
	v_rcp_f32_e32 v30, v30
	v_rcp_f32_e32 v31, v31
	s_nop 0
	v_pk_mul_f32 v[28:29], v[28:29], v[30:31]
	s_nop 0
	v_pk_mul_f32 v[26:27], v[26:27], v[28:29]
	v_mul_f32_e32 v28, 0xbfb8aa3b, v20
	v_mul_f32_e32 v29, 0xbfb8aa3b, v21
	v_exp_f32_e32 v28, v28
	v_exp_f32_e32 v29, v29
	v_add_f32_e32 v28, 1.0, v28
	v_add_f32_e32 v29, 1.0, v29
	v_rcp_f32_e32 v28, v28
	v_rcp_f32_e32 v29, v29
	s_nop 0
	v_pk_mul_f32 v[20:21], v[20:21], v[28:29]
	s_nop 0
	v_pk_mul_f32 v[20:21], v[16:17], v[20:21]
	v_pk_mul_f32 v[16:17], v[22:23], v[32:33] op_sel_hi:[1,0]
	s_nop 0
	v_mul_f32_e32 v22, 0xbfb8aa3b, v16
	v_mul_f32_e32 v23, 0xbfb8aa3b, v17
	v_exp_f32_e32 v22, v22
	v_exp_f32_e32 v23, v23
	v_add_f32_e32 v22, 1.0, v22
	v_add_f32_e32 v23, 1.0, v23
	v_rcp_f32_e32 v22, v22
	v_rcp_f32_e32 v23, v23
	s_nop 0
	v_pk_mul_f32 v[16:17], v[16:17], v[22:23]
	s_nop 0
	v_pk_mul_f32 v[22:23], v[18:19], v[16:17]
	v_add_u32_e32 v150, 0x16000, v150
	v_cvt_pk_bf16_f32 v16, v24, v25
	v_cvt_pk_bf16_f32 v17, v26, v27
	v_cvt_pk_bf16_f32 v18, v20, v21
	v_cvt_pk_bf16_f32 v19, v22, v23
	global_store_dwordx4 v150, v[16:19], s[6:7]
	s_cbranch_vccnz .LBB0_278
	ds_read_b32 v44, v144 offset:704
.LBB0_278:
	s_waitcnt lgkmcnt(0)
	v_pk_mul_f32 v[12:13], v[12:13], v[44:45] op_sel_hi:[1,0]
	v_pk_mul_f32 v[8:9], v[8:9], v[44:45] op_sel_hi:[1,0]
	v_mul_f32_e32 v16, 0xbfb8aa3b, v12
	v_mul_f32_e32 v17, 0xbfb8aa3b, v13
	v_exp_f32_e32 v16, v16
	v_exp_f32_e32 v17, v17
	v_pk_mul_f32 v[10:11], v[10:11], v[44:45] op_sel_hi:[1,0]
	v_pk_mul_f32 v[4:5], v[4:5], v[44:45] op_sel_hi:[1,0]
	v_add_f32_e32 v16, 1.0, v16
	v_add_f32_e32 v17, 1.0, v17
	v_rcp_f32_e32 v16, v16
	v_rcp_f32_e32 v17, v17
	v_pk_mul_f32 v[0:1], v[0:1], v[44:45] op_sel_hi:[1,0]
	v_pk_mul_f32 v[2:3], v[2:3], v[44:45] op_sel_hi:[1,0]
	v_add_u32_e32 v18, 0xb0, v145
	v_pk_mul_f32 v[12:13], v[12:13], v[16:17]
	s_andn2_b64 vcc, exec, s[4:5]
	v_pk_mul_f32 v[8:9], v[8:9], v[12:13]
	v_pk_mul_f32 v[12:13], v[14:15], v[44:45] op_sel_hi:[1,0]
	s_nop 0
	v_mul_f32_e32 v14, 0xbfb8aa3b, v12
	v_mul_f32_e32 v15, 0xbfb8aa3b, v13
	v_exp_f32_e32 v14, v14
	v_exp_f32_e32 v15, v15
	v_add_f32_e32 v14, 1.0, v14
	v_add_f32_e32 v15, 1.0, v15
	v_rcp_f32_e32 v14, v14
	v_rcp_f32_e32 v15, v15
	s_nop 0
	v_pk_mul_f32 v[12:13], v[12:13], v[14:15]
	s_nop 0
	v_pk_mul_f32 v[10:11], v[10:11], v[12:13]
	v_mul_f32_e32 v12, 0xbfb8aa3b, v4
	v_mul_f32_e32 v13, 0xbfb8aa3b, v5
	v_exp_f32_e32 v12, v12
	v_exp_f32_e32 v13, v13
	v_add_f32_e32 v12, 1.0, v12
	v_add_f32_e32 v13, 1.0, v13
	v_rcp_f32_e32 v12, v12
	v_rcp_f32_e32 v13, v13
	s_nop 0
	v_pk_mul_f32 v[4:5], v[4:5], v[12:13]
	s_nop 0
	v_pk_mul_f32 v[4:5], v[0:1], v[4:5]
	v_pk_mul_f32 v[0:1], v[6:7], v[44:45] op_sel_hi:[1,0]
	s_nop 0
	v_mul_f32_e32 v6, 0xbfb8aa3b, v0
	v_mul_f32_e32 v7, 0xbfb8aa3b, v1
	v_exp_f32_e32 v6, v6
	v_exp_f32_e32 v7, v7
	v_add_f32_e32 v6, 1.0, v6
	v_add_f32_e32 v7, 1.0, v7
	v_rcp_f32_e32 v6, v6
	v_rcp_f32_e32 v7, v7
	s_nop 0
	v_pk_mul_f32 v[0:1], v[0:1], v[6:7]
	s_nop 0
	v_pk_mul_f32 v[6:7], v[2:3], v[0:1]
	v_add_u32_e32 v150, 0x16000, v150
	v_cvt_pk_bf16_f32 v0, v8, v9
	v_cvt_pk_bf16_f32 v1, v10, v11
	v_cvt_pk_bf16_f32 v2, v4, v5
	v_cvt_pk_bf16_f32 v3, v6, v7
	s_mov_b64 s[0:1], -1
	global_store_dwordx4 v150, v[0:3], s[6:7]
	s_cbranch_vccnz .LBB0_249
	s_andn2_b64 vcc, exec, s[2:3]
	s_cbranch_vccnz .LBB0_248
	s_barrier
	s_branch .LBB0_248
